# differential loop role B: staging stores and next loads issued between its PV and QK MFMA phases (role A is in its softmax then, nobody else reads LDS), no LDS-write wait left in role B's tail
# speedup vs baseline: 1.0074x; 1.0074x over previous
; template <bool DIFF>
; __device__ __forceinline__ void attn_unit(const AttnP& A, int b, int h, int qi, ldsp lds) {
;     ...
;             QK_BLOCK();
;             s16x4 vlo[8], vhi[8];
; #pragma unroll
;             for (int t = 0; t < 2; ++t)
; #pragma unroll
;     ...
;             l_run += psa + psb;
;     ...
;             bf16x8 pw[4];
; #pragma unroll
;             for (int j = 0; j < 4; ++j) {
;                 u32x4 pk;
;                 if (j < 2) { const int rb = 8 * (j & 1); pk.x = cvtpk(s0[rb], s0[rb + 1]); pk.y = cvtpk(s0[rb + 2], s0[rb + 3]); pk.z = cvtpk(s0[rb + 4], s0[rb + 5]); pk.w = cvtpk(s0[rb + 6], s0[rb + 7]); }
;                 else { const int rb = 8 * (j & 1); pk.x = cvtpk(s1[rb], s1[rb + 1]); pk.y = cvtpk(s1[rb + 2], s1[rb + 3]); pk.z = cvtpk(s1[rb + 4], s1[rb + 5]); pk.w = cvtpk(s1[rb + 6], s1[rb + 7]); }
;                 pw[j] = __builtin_bit_cast(bf16x8, pk);
;             }
;             __builtin_amdgcn_sched_barrier(0);
;             __builtin_amdgcn_s_setprio(1);
; #pragma unroll
;             for (int t = 0; t < 2; ++t)
; #pragma unroll
;                 for (int j = 0; j < 4; ++j) {
;                     const bf16x8 vf = (bf16x8){vlo[t * 4 + j][0], vlo[t * 4 + j][1], vlo[t * 4 + j][2], vlo[t * 4 + j][3], vhi[t * 4 + j][0], vhi[t * 4 + j][1], vhi[t * 4 + j][2], vhi[t * 4 + j][3]};
;                     o[t] = __builtin_amdgcn_mfma_f32_32x32x16_bf16(vf, pw[j], o[t], 0, 0, 0);
;                 }
;             if (DIFF) {
; #pragma unroll
;                 for (int t = 2; t < NTD; ++t)
; #pragma unroll
;                     for (int j = 0; j < 4; ++j) { vlo[(t - 2) * 4 + j] = vtr(Vb + trb + (16 * j) * VP + t * 64); vhi[(t - 2) * 4 + j] = vtr(Vb + trb + (16 * j + 8) * VP + t * 64); }
;                 __builtin_amdgcn_sched_barrier(0);
; #pragma unroll
;                 for (int t = 2; t < NTD; ++t)
; #pragma unroll
;                     for (int j = 0; j < 4; ++j) {
;                         const int i = (t - 2) * 4 + j;
;                         const bf16x8 vf = (bf16x8){vlo[i][0], vlo[i][1], vlo[i][2], vlo[i][3], vhi[i][0], vhi[i][1], vhi[i][2], vhi[i][3]};
;                         o[t] = __builtin_amdgcn_mfma_f32_32x32x16_bf16(vf, pw[j], o[t], 0, 0, 0);
;                     }
;             }
;             __builtin_amdgcn_s_setprio(0);
.Ldb_s_even:
	v_exp_f32_e32 v148, v98
	v_exp_f32_e32 v164, v82
	v_exp_f32_e32 v149, v99
	v_exp_f32_e32 v165, v83
	v_add_f32_e32 v237, 0, v148
	v_add_f32_e32 v238, 0, v164
	v_exp_f32_e32 v150, v100
	v_exp_f32_e32 v166, v84
	v_add_f32_e32 v237, v149, v237
	v_add_f32_e32 v238, v165, v238
	v_exp_f32_e32 v151, v101
	v_exp_f32_e32 v167, v85
	v_add_f32_e32 v237, v150, v237
	v_add_f32_e32 v238, v166, v238
	v_exp_f32_e32 v152, v102
	v_exp_f32_e32 v168, v86
	v_add_f32_e32 v237, v151, v237
	v_add_f32_e32 v238, v167, v238
	v_exp_f32_e32 v153, v103
	v_exp_f32_e32 v169, v87
	v_add_f32_e32 v237, v152, v237
	v_add_f32_e32 v238, v168, v238
	v_exp_f32_e32 v154, v104
	v_exp_f32_e32 v170, v88
	v_add_f32_e32 v237, v153, v237
	v_add_f32_e32 v238, v169, v238
	v_exp_f32_e32 v155, v105
	v_exp_f32_e32 v171, v89
	v_add_f32_e32 v237, v154, v237
	v_add_f32_e32 v238, v170, v238
	v_exp_f32_e32 v156, v106
	v_exp_f32_e32 v172, v90
	v_add_f32_e32 v237, v155, v237
	v_add_f32_e32 v238, v171, v238
	v_exp_f32_e32 v157, v107
	v_exp_f32_e32 v173, v91
	v_add_f32_e32 v237, v156, v237
	v_add_f32_e32 v238, v172, v238
	v_exp_f32_e32 v158, v108
	v_exp_f32_e32 v174, v92
	v_add_f32_e32 v237, v157, v237
	v_add_f32_e32 v238, v173, v238
	v_exp_f32_e32 v159, v109
	v_exp_f32_e32 v175, v93
	v_add_f32_e32 v237, v158, v237
	v_add_f32_e32 v238, v174, v238
	v_exp_f32_e32 v160, v110
	v_exp_f32_e32 v176, v94
	v_add_f32_e32 v237, v159, v237
	v_add_f32_e32 v238, v175, v238
	v_exp_f32_e32 v161, v111
	v_exp_f32_e32 v177, v95
	v_add_f32_e32 v237, v160, v237
	v_add_f32_e32 v238, v176, v238
	v_exp_f32_e32 v162, v112
	v_exp_f32_e32 v178, v96
	v_add_f32_e32 v237, v161, v237
	v_add_f32_e32 v238, v177, v238
	v_exp_f32_e32 v163, v113
	v_exp_f32_e32 v179, v97
	v_add_f32_e32 v237, v162, v237
	v_add_f32_e32 v238, v178, v238
	s_nop 0
	v_add_f32_e32 v237, v163, v237
	v_add_f32_e32 v238, v179, v238
	v_add_f32_e32 v204, v237, v238
	v_cmp_lt_f32_e32 vcc, s85, v204
	s_cbranch_vccnz .Ldb_s_slow
	ds_read_b64_tr_b16 v[90:91], v252 offset:17472
	ds_read_b64_tr_b16 v[92:93], v252 offset:20032
	ds_read_b64_tr_b16 v[94:95], v252 offset:17408
	ds_read_b64_tr_b16 v[96:97], v252 offset:19968
	ds_read_b64_tr_b16 v[106:107], v252 offset:22592
	ds_read_b64_tr_b16 v[108:109], v252 offset:25152
	ds_read_b64_tr_b16 v[110:111], v252 offset:22528
	ds_read_b64_tr_b16 v[112:113], v252 offset:25088
	ds_read_b64_tr_b16 v[240:241], v252 offset:27712
	ds_read_b64_tr_b16 v[242:243], v252 offset:30272
	v_cvt_pk_bf16_f32 v98, v148, v149
	v_cvt_pk_bf16_f32 v99, v150, v151
	v_cvt_pk_bf16_f32 v100, v152, v153
	v_cvt_pk_bf16_f32 v101, v154, v155
	v_cvt_pk_bf16_f32 v102, v156, v157
	v_cvt_pk_bf16_f32 v103, v158, v159
	v_cvt_pk_bf16_f32 v104, v160, v161
	v_cvt_pk_bf16_f32 v105, v162, v163
	v_cvt_pk_bf16_f32 v82, v164, v165
	v_cvt_pk_bf16_f32 v83, v166, v167
	v_cvt_pk_bf16_f32 v84, v168, v169
	v_cvt_pk_bf16_f32 v85, v170, v171
	v_cvt_pk_bf16_f32 v86, v172, v173
	v_cvt_pk_bf16_f32 v87, v174, v175
	v_cvt_pk_bf16_f32 v88, v176, v177
	v_cvt_pk_bf16_f32 v89, v178, v179
	v_add_f32_e32 v230, v204, v230
	ds_read_b64_tr_b16 v[148:149], v252 offset:27648
	ds_read_b64_tr_b16 v[150:151], v252 offset:30208
	ds_read_b64_tr_b16 v[152:153], v252 offset:32768
	ds_read_b64_tr_b16 v[154:155], v252 offset:35328
	ds_read_b64_tr_b16 v[156:157], v252 offset:32832
	ds_read_b64_tr_b16 v[158:159], v252 offset:35392
	s_setprio 1
	s_waitcnt lgkmcnt(14)
	v_mfma_f32_32x32x16_bf16 v[34:49], v[90:93], v[98:101], v[34:49]
	ds_read_b64_tr_b16 v[160:161], v252 offset:17536
	ds_read_b64_tr_b16 v[162:163], v252 offset:20096
	s_waitcnt lgkmcnt(14)
	v_mfma_f32_32x32x16_bf16 v[50:65], v[94:97], v[98:101], v[50:65]
	ds_read_b64_tr_b16 v[164:165], v252 offset:17600
	ds_read_b64_tr_b16 v[166:167], v252 offset:20160
	s_waitcnt lgkmcnt(14)
	v_mfma_f32_32x32x16_bf16 v[34:49], v[106:109], v[102:105], v[34:49]
	ds_read_b64_tr_b16 v[168:169], v252 offset:22656
	ds_read_b64_tr_b16 v[170:171], v252 offset:25216
	s_waitcnt lgkmcnt(14)
	v_mfma_f32_32x32x16_bf16 v[50:65], v[110:113], v[102:105], v[50:65]
	ds_read_b64_tr_b16 v[172:173], v252 offset:22720
	ds_read_b64_tr_b16 v[174:175], v252 offset:25280
	s_waitcnt lgkmcnt(14)
	v_mfma_f32_32x32x16_bf16 v[34:49], v[240:243], v[82:85], v[34:49]
	ds_read_b64_tr_b16 v[176:177], v252 offset:27776
	ds_read_b64_tr_b16 v[178:179], v252 offset:30336
	s_waitcnt lgkmcnt(14)
	v_mfma_f32_32x32x16_bf16 v[50:65], v[148:151], v[82:85], v[50:65]
	ds_read_b64_tr_b16 v[90:91], v252 offset:27840
	ds_read_b64_tr_b16 v[92:93], v252 offset:30400
	s_waitcnt lgkmcnt(14)
	v_mfma_f32_32x32x16_bf16 v[50:65], v[152:155], v[86:89], v[50:65]
	ds_read_b64_tr_b16 v[94:95], v252 offset:32896
	ds_read_b64_tr_b16 v[96:97], v252 offset:35456
	s_waitcnt lgkmcnt(14)
	v_mfma_f32_32x32x16_bf16 v[34:49], v[156:159], v[86:89], v[34:49]
	ds_read_b64_tr_b16 v[106:107], v252 offset:32960
	ds_read_b64_tr_b16 v[108:109], v252 offset:35520
	s_waitcnt lgkmcnt(14)
	v_mfma_f32_32x32x16_bf16 v[18:33], v[160:163], v[98:101], v[18:33]
	ds_read_b128 v[240:243], v234
	s_waitcnt lgkmcnt(13)
	v_mfma_f32_32x32x16_bf16 v[2:17], v[164:167], v[98:101], v[2:17]
	ds_read_b128 v[148:151], v234 offset:8704
	s_waitcnt lgkmcnt(12)
	v_mfma_f32_32x32x16_bf16 v[18:33], v[168:171], v[102:105], v[18:33]
	ds_read_b128 v[152:155], v234 offset:32
	s_waitcnt lgkmcnt(11)
	v_mfma_f32_32x32x16_bf16 v[2:17], v[172:175], v[102:105], v[2:17]
	ds_read_b128 v[156:159], v234 offset:8736
	s_waitcnt lgkmcnt(10)
	v_mfma_f32_32x32x16_bf16 v[18:33], v[176:179], v[82:85], v[18:33]
	ds_read_b128 v[160:163], v234 offset:64
	s_waitcnt lgkmcnt(9)
	v_mfma_f32_32x32x16_bf16 v[2:17], v[90:93], v[82:85], v[2:17]
	ds_read_b128 v[164:167], v234 offset:8768
	s_waitcnt lgkmcnt(8)
; __device__ __forceinline__ s16x4 vtr(ldsp p) { return __builtin_bit_cast(s16x4, __builtin_amdgcn_ds_read_tr16_b64_v4i16((LAS v4i16_t*)p)); }
; #define MASK_BLOCK() do { if (kt == 0 || kt >= diag0) { \
;             _Pragma("unroll") for (int r = 0; r < 16; ++r) { const int kpp = 64 * kt + crow(r, hi); \
;                 if (kpp < 48 || kpp > q_pp) s0[r] = -INFINITY; \
;                 if (kpp + 32 < 48 || kpp + 32 > q_pp) s1[r] = -INFINITY; } } } while (0)
; #define EXPSUM_BLOCK() do { psa = 0.f; psb = 0.f; \
;             _Pragma("unroll") for (int r = 0; r < 16; ++r) { s0[r] = __builtin_amdgcn_exp2f(s0[r]); s1[r] = __builtin_amdgcn_exp2f(s1[r]); psa += s0[r]; asm("" : "+v"(psa)); psb += s1[r]; asm("" : "+v"(psb)); } } while (0)
; template <bool DIFF>
; __device__ __forceinline__ void attn_unit(const AttnP& A, int b, int h, int qi, ldsp lds) {
;     ...
;             QK_BLOCK();
;             s16x4 vlo[8], vhi[8];
; #pragma unroll
;             for (int t = 0; t < 2; ++t)
; #pragma unroll
;                 for (int j = 0; j < 4; ++j) { vlo[t * 4 + j] = vtr(Vb + trb + (16 * j) * VP + t * 64); vhi[t * 4 + j] = vtr(Vb + trb + (16 * j + 8) * VP + t * 64); }
;             __builtin_amdgcn_sched_barrier(0);
;             MASK_BLOCK();
;             bool full = (kt == kt0);
;             float psa, psb;
;             if (!full) {
;                 EXPSUM_BLOCK();
;                 if (__any(psa + psb > 1.0e18f)) { full = true; QK_BLOCK();
	v_mfma_f32_32x32x16_bf16 v[18:33], v[94:97], v[86:89], v[18:33]
	ds_read_b128 v[168:171], v234 offset:96
	s_waitcnt lgkmcnt(7)
	v_mfma_f32_32x32x16_bf16 v[2:17], v[106:109], v[86:89], v[2:17]
	ds_read_b128 v[172:175], v234 offset:8800
	s_waitcnt vmcnt(0)
	ds_write_b128 v226, v[132:135] offset:38144
	ds_write_b128 v228, v[140:143] offset:38144
	ds_write_b128 v227, v[136:139] offset:17408
	ds_write_b128 v229, v[144:147] offset:17408
	global_load_dwordx4 v[136:139], v[196:197], off offset:2048
	global_load_dwordx4 v[144:147], v[198:199], off offset:2048
	v_lshl_add_u64 v[196:197], v[196:197], 0, s[26:27]
	v_lshl_add_u64 v[198:199], v[198:199], 0, s[26:27]
	global_load_dwordx4 v[132:135], v[196:197], off offset:1024
	global_load_dwordx4 v[140:143], v[198:199], off offset:1024
	s_waitcnt lgkmcnt(11)
	v_mfma_f32_32x32x16_bf16 v[98:113], v[240:243], v[116:119], v[66:81]
	s_waitcnt lgkmcnt(10)
	v_mfma_f32_32x32x16_bf16 v[82:97], v[148:151], v[116:119], v[66:81]
	s_waitcnt lgkmcnt(9)
	v_mfma_f32_32x32x16_bf16 v[98:113], v[152:155], v[120:123], v[98:113]
	s_waitcnt lgkmcnt(8)
	v_mfma_f32_32x32x16_bf16 v[82:97], v[156:159], v[120:123], v[82:97]
	s_waitcnt lgkmcnt(7)
	v_mfma_f32_32x32x16_bf16 v[98:113], v[160:163], v[124:127], v[98:113]
	s_waitcnt lgkmcnt(6)
	v_mfma_f32_32x32x16_bf16 v[82:97], v[164:167], v[124:127], v[82:97]
	s_waitcnt lgkmcnt(5)
	v_mfma_f32_32x32x16_bf16 v[98:113], v[168:171], v[128:131], v[98:113]
	s_waitcnt lgkmcnt(4)
	v_mfma_f32_32x32x16_bf16 v[82:97], v[172:175], v[128:131], v[82:97]
	s_setprio 0
	s_waitcnt lgkmcnt(0)
	s_barrier
	s_add_i32 s75, s75, 1
	s_add_i32 s74, s74, 64
	s_cmp_gt_i32 s75, s23
	s_cbranch_scc1 .Ldb_gen
.Ldb_s_odd:
	v_exp_f32_e32 v148, v98
	v_exp_f32_e32 v164, v82
	v_exp_f32_e32 v149, v99
	v_exp_f32_e32 v165, v83
	v_add_f32_e32 v237, 0, v148
	v_add_f32_e32 v238, 0, v164
	v_exp_f32_e32 v150, v100
	v_exp_f32_e32 v166, v84
	v_add_f32_e32 v237, v149, v237
	v_add_f32_e32 v238, v165, v238
	v_exp_f32_e32 v151, v101
	v_exp_f32_e32 v167, v85
	v_add_f32_e32 v237, v150, v237
	v_add_f32_e32 v238, v166, v238
	v_exp_f32_e32 v152, v102
	v_exp_f32_e32 v168, v86
	v_add_f32_e32 v237, v151, v237
	v_add_f32_e32 v238, v167, v238
	v_exp_f32_e32 v153, v103
	v_exp_f32_e32 v169, v87
	v_add_f32_e32 v237, v152, v237
	v_add_f32_e32 v238, v168, v238
	v_exp_f32_e32 v154, v104
	v_exp_f32_e32 v170, v88
	v_add_f32_e32 v237, v153, v237
	v_add_f32_e32 v238, v169, v238
	v_exp_f32_e32 v155, v105
	v_exp_f32_e32 v171, v89
	v_add_f32_e32 v237, v154, v237
	v_add_f32_e32 v238, v170, v238
	v_exp_f32_e32 v156, v106
	v_exp_f32_e32 v172, v90
	v_add_f32_e32 v237, v155, v237
	v_add_f32_e32 v238, v171, v238
	v_exp_f32_e32 v157, v107
	v_exp_f32_e32 v173, v91
	v_add_f32_e32 v237, v156, v237
	v_add_f32_e32 v238, v172, v238
	v_exp_f32_e32 v158, v108
	v_exp_f32_e32 v174, v92
	v_add_f32_e32 v237, v157, v237
	v_add_f32_e32 v238, v173, v238
	v_exp_f32_e32 v159, v109
	v_exp_f32_e32 v175, v93
	v_add_f32_e32 v237, v158, v237
	v_add_f32_e32 v238, v174, v238
	v_exp_f32_e32 v160, v110
	v_exp_f32_e32 v176, v94
	v_add_f32_e32 v237, v159, v237
	v_add_f32_e32 v238, v175, v238
	v_exp_f32_e32 v161, v111
	v_exp_f32_e32 v177, v95
	v_add_f32_e32 v237, v160, v237
	v_add_f32_e32 v238, v176, v238
	v_exp_f32_e32 v162, v112
	v_exp_f32_e32 v178, v96
	v_add_f32_e32 v237, v161, v237
	v_add_f32_e32 v238, v177, v238
	v_exp_f32_e32 v163, v113
	v_exp_f32_e32 v179, v97
	v_add_f32_e32 v237, v162, v237
	v_add_f32_e32 v238, v178, v238
	s_nop 0
	v_add_f32_e32 v237, v163, v237
	v_add_f32_e32 v238, v179, v238
	v_add_f32_e32 v204, v237, v238
	v_cmp_lt_f32_e32 vcc, s85, v204
	s_cbranch_vccnz .Ldb_s_slow
; __device__ __forceinline__ unsigned cvtpk(float lo, float hi) { f32x2 v = {lo, hi}; bf16x2_t b = __builtin_convertvector(v, bf16x2_t); return __builtin_bit_cast(unsigned, b); }
; template <bool DIFF>
; __device__ __forceinline__ void attn_unit(const AttnP& A, int b, int h, int qi, ldsp lds) {
;     ...
;             bf16x8 pw[4];
; #pragma unroll
;             for (int j = 0; j < 4; ++j) {
;                 u32x4 pk;
;                 if (j < 2) { const int rb = 8 * (j & 1); pk.x = cvtpk(s0[rb], s0[rb + 1]); pk.y = cvtpk(s0[rb + 2], s0[rb + 3]); pk.z = cvtpk(s0[rb + 4], s0[rb + 5]); pk.w = cvtpk(s0[rb + 6], s0[rb + 7]); }
;                 else { const int rb = 8 * (j & 1); pk.x = cvtpk(s1[rb], s1[rb + 1]); pk.y = cvtpk(s1[rb + 2], s1[rb + 3]); pk.z = cvtpk(s1[rb + 4], s1[rb + 5]); pk.w = cvtpk(s1[rb + 6], s1[rb + 7]); }
;                 pw[j] = __builtin_bit_cast(bf16x8, pk);
;             }
;             __builtin_amdgcn_sched_barrier(0);
;             __builtin_amdgcn_s_setprio(1);
; #pragma unroll
;             for (int t = 0; t < 2; ++t)
; #pragma unroll
;                 for (int j = 0; j < 4; ++j) {
;                     const bf16x8 vf = (bf16x8){vlo[t * 4 + j][0], vlo[t * 4 + j][1], vlo[t * 4 + j][2], vlo[t * 4 + j][3], vhi[t * 4 + j][0], vhi[t * 4 + j][1], vhi[t * 4 + j][2], vhi[t * 4 + j][3]};
;                     o[t] = __builtin_amdgcn_mfma_f32_32x32x16_bf16(vf, pw[j], o[t], 0, 0, 0);
;                 }
;             if (DIFF) {
; #pragma unroll
;                 for (int t = 2; t < NTD; ++t)
; #pragma unroll
;                     for (int j = 0; j < 4; ++j) { vlo[(t - 2) * 4 + j] = vtr(Vb + trb + (16 * j) * VP + t * 64); vhi[(t - 2) * 4 + j] = vtr(Vb + trb + (16 * j + 8) * VP + t * 64); }
;                 __builtin_amdgcn_sched_barrier(0);
; #pragma unroll
;                 for (int t = 2; t < NTD; ++t)
; #pragma unroll
;                     for (int j = 0; j < 4; ++j) {
;                         const int i = (t - 2) * 4 + j;
;                         const bf16x8 vf = (bf16x8){vlo[i][0], vlo[i][1], vlo[i][2], vlo[i][3], vhi[i][0], vhi[i][1], vhi[i][2], vhi[i][3]};
;                         o[t] = __builtin_amdgcn_mfma_f32_32x32x16_bf16(vf, pw[j], o[t], 0, 0, 0);
;                     }
;             }
;             __builtin_amdgcn_s_setprio(0);
	ds_read_b64_tr_b16 v[90:91], v231 offset:17472
	ds_read_b64_tr_b16 v[92:93], v231 offset:20032
	ds_read_b64_tr_b16 v[94:95], v231 offset:17408
	ds_read_b64_tr_b16 v[96:97], v231 offset:19968
	ds_read_b64_tr_b16 v[106:107], v231 offset:22592
	ds_read_b64_tr_b16 v[108:109], v231 offset:25152
	ds_read_b64_tr_b16 v[110:111], v231 offset:22528
	ds_read_b64_tr_b16 v[112:113], v231 offset:25088
	ds_read_b64_tr_b16 v[240:241], v231 offset:27712
	ds_read_b64_tr_b16 v[242:243], v231 offset:30272
	v_cvt_pk_bf16_f32 v98, v148, v149
	v_cvt_pk_bf16_f32 v99, v150, v151
	v_cvt_pk_bf16_f32 v100, v152, v153
	v_cvt_pk_bf16_f32 v101, v154, v155
	v_cvt_pk_bf16_f32 v102, v156, v157
	v_cvt_pk_bf16_f32 v103, v158, v159
	v_cvt_pk_bf16_f32 v104, v160, v161
	v_cvt_pk_bf16_f32 v105, v162, v163
	v_cvt_pk_bf16_f32 v82, v164, v165
	v_cvt_pk_bf16_f32 v83, v166, v167
	v_cvt_pk_bf16_f32 v84, v168, v169
	v_cvt_pk_bf16_f32 v85, v170, v171
	v_cvt_pk_bf16_f32 v86, v172, v173
	v_cvt_pk_bf16_f32 v87, v174, v175
	v_cvt_pk_bf16_f32 v88, v176, v177
	v_cvt_pk_bf16_f32 v89, v178, v179
	v_add_f32_e32 v230, v204, v230
	ds_read_b64_tr_b16 v[148:149], v231 offset:27648
	ds_read_b64_tr_b16 v[150:151], v231 offset:30208
	ds_read_b64_tr_b16 v[152:153], v231 offset:32768
	ds_read_b64_tr_b16 v[154:155], v231 offset:35328
	ds_read_b64_tr_b16 v[156:157], v231 offset:32832
	ds_read_b64_tr_b16 v[158:159], v231 offset:35392
	s_setprio 1
	s_waitcnt lgkmcnt(14)
	v_mfma_f32_32x32x16_bf16 v[34:49], v[90:93], v[98:101], v[34:49]
	ds_read_b64_tr_b16 v[160:161], v231 offset:17536
	ds_read_b64_tr_b16 v[162:163], v231 offset:20096
	s_waitcnt lgkmcnt(14)
	v_mfma_f32_32x32x16_bf16 v[50:65], v[94:97], v[98:101], v[50:65]
	ds_read_b64_tr_b16 v[164:165], v231 offset:17600
	ds_read_b64_tr_b16 v[166:167], v231 offset:20160
	s_waitcnt lgkmcnt(14)
	v_mfma_f32_32x32x16_bf16 v[34:49], v[106:109], v[102:105], v[34:49]
	ds_read_b64_tr_b16 v[168:169], v231 offset:22656
	ds_read_b64_tr_b16 v[170:171], v231 offset:25216
	s_waitcnt lgkmcnt(14)
	v_mfma_f32_32x32x16_bf16 v[50:65], v[110:113], v[102:105], v[50:65]
	ds_read_b64_tr_b16 v[172:173], v231 offset:22720
	ds_read_b64_tr_b16 v[174:175], v231 offset:25280
	s_waitcnt lgkmcnt(14)
	v_mfma_f32_32x32x16_bf16 v[34:49], v[240:243], v[82:85], v[34:49]
	ds_read_b64_tr_b16 v[176:177], v231 offset:27776
	ds_read_b64_tr_b16 v[178:179], v231 offset:30336
	s_waitcnt lgkmcnt(14)
	v_mfma_f32_32x32x16_bf16 v[50:65], v[148:151], v[82:85], v[50:65]
	ds_read_b64_tr_b16 v[90:91], v231 offset:27840
	ds_read_b64_tr_b16 v[92:93], v231 offset:30400
	s_waitcnt lgkmcnt(14)
	v_mfma_f32_32x32x16_bf16 v[50:65], v[152:155], v[86:89], v[50:65]
	ds_read_b64_tr_b16 v[94:95], v231 offset:32896
	ds_read_b64_tr_b16 v[96:97], v231 offset:35456
	s_waitcnt lgkmcnt(14)
	v_mfma_f32_32x32x16_bf16 v[34:49], v[156:159], v[86:89], v[34:49]
	ds_read_b64_tr_b16 v[106:107], v231 offset:32960
	ds_read_b64_tr_b16 v[108:109], v231 offset:35520
	s_waitcnt lgkmcnt(14)
	v_mfma_f32_32x32x16_bf16 v[18:33], v[160:163], v[98:101], v[18:33]
	ds_read_b128 v[240:243], v234 offset:38144
	s_waitcnt lgkmcnt(13)
	v_mfma_f32_32x32x16_bf16 v[2:17], v[164:167], v[98:101], v[2:17]
	ds_read_b128 v[148:151], v234 offset:46848
	s_waitcnt lgkmcnt(12)
	v_mfma_f32_32x32x16_bf16 v[18:33], v[168:171], v[102:105], v[18:33]
	ds_read_b128 v[152:155], v234 offset:38176
	s_waitcnt lgkmcnt(11)
	v_mfma_f32_32x32x16_bf16 v[2:17], v[172:175], v[102:105], v[2:17]
	ds_read_b128 v[156:159], v234 offset:46880
	s_waitcnt lgkmcnt(10)
	v_mfma_f32_32x32x16_bf16 v[18:33], v[176:179], v[82:85], v[18:33]
	ds_read_b128 v[160:163], v234 offset:38208
	s_waitcnt lgkmcnt(9)
	v_mfma_f32_32x32x16_bf16 v[2:17], v[90:93], v[82:85], v[2:17]
	ds_read_b128 v[164:167], v234 offset:46912
	s_waitcnt lgkmcnt(8)
	v_mfma_f32_32x32x16_bf16 v[18:33], v[94:97], v[86:89], v[18:33]
	ds_read_b128 v[168:171], v234 offset:38240
	s_waitcnt lgkmcnt(7)
	v_mfma_f32_32x32x16_bf16 v[2:17], v[106:109], v[86:89], v[2:17]
	ds_read_b128 v[172:175], v234 offset:46944
	s_waitcnt vmcnt(0)
	ds_write_b128 v226, v[132:135]
	ds_write_b128 v228, v[140:143]
	ds_write_b128 v227, v[136:139] offset:55552
	ds_write_b128 v229, v[144:147] offset:55552
	global_load_dwordx4 v[136:139], v[196:197], off offset:2048
	global_load_dwordx4 v[144:147], v[198:199], off offset:2048
	v_lshl_add_u64 v[196:197], v[196:197], 0, s[26:27]
	v_lshl_add_u64 v[198:199], v[198:199], 0, s[26:27]
	global_load_dwordx4 v[132:135], v[196:197], off offset:1024
	global_load_dwordx4 v[140:143], v[198:199], off offset:1024
	s_waitcnt lgkmcnt(11)
	v_mfma_f32_32x32x16_bf16 v[98:113], v[240:243], v[116:119], v[66:81]
	s_waitcnt lgkmcnt(10)
	v_mfma_f32_32x32x16_bf16 v[82:97], v[148:151], v[116:119], v[66:81]
	s_waitcnt lgkmcnt(9)
	v_mfma_f32_32x32x16_bf16 v[98:113], v[152:155], v[120:123], v[98:113]
	s_waitcnt lgkmcnt(8)
	v_mfma_f32_32x32x16_bf16 v[82:97], v[156:159], v[120:123], v[82:97]
	s_waitcnt lgkmcnt(7)
	v_mfma_f32_32x32x16_bf16 v[98:113], v[160:163], v[124:127], v[98:113]
	s_waitcnt lgkmcnt(6)
	v_mfma_f32_32x32x16_bf16 v[82:97], v[164:167], v[124:127], v[82:97]
	s_waitcnt lgkmcnt(5)
	v_mfma_f32_32x32x16_bf16 v[98:113], v[168:171], v[128:131], v[98:113]
	s_waitcnt lgkmcnt(4)
	v_mfma_f32_32x32x16_bf16 v[82:97], v[172:175], v[128:131], v[82:97]
	s_setprio 0
	s_waitcnt lgkmcnt(0)
	s_barrier
	s_add_i32 s75, s75, 1
	s_add_i32 s74, s74, 64
	s_cmp_le_i32 s75, s23
	s_cbranch_scc1 .Ldb_s_even
